# per-phase steal limit: in-proj GEMM phase leaves after its own queue fails (uniform tiles, identical queues); other phases keep 2 queue visits
# baseline (speedup 1.0000x reference)
.LBB0_198:
	s_or_b64 exec, exec, s[4:5]
	s_waitcnt lgkmcnt(0)
	s_barrier
	ds_read_b32 v0, v103
	s_movk_i32 s4, 0x1b0
	s_waitcnt lgkmcnt(0)
	v_cmp_gt_i32_e32 vcc, s4, v0
	v_readfirstlane_b32 s6, v0
	s_mov_b64 s[4:5], 0
	s_cbranch_vccnz .LBB0_201
	v_mov_b32_e32 v0, 0x12004
	ds_read_b32 v0, v0
	s_waitcnt lgkmcnt(0)
	v_readfirstlane_b32 s4, v0
	s_cmp_eq_u32 s4, 8
	s_cselect_b32 s4, -1, 6
	s_cmp_gt_i32 s47, s4
	s_mov_b32 s4, 0
	s_cbranch_scc1 .LBB0_202
	s_add_i32 s4, s37, 1
	s_and_b32 s37, s4, 7
	s_add_i32 s47, s47, 1
	s_cbranch_execnz .LBB0_194
	s_branch .LBB0_203
